# combined: attention prologue one-window loads + per-wave max-test skip, LRU pass-3 aggregate loads one window, work-queue index prefetch, P0 odd waves RMSNorm-first
# speedup vs baseline: 1.0092x; 1.0092x over previous
; #define LAS __attribute__((address_space(3)))
; #define KA() ({ KArgs p_ = (KArgs)__builtin_amdgcn_kernarg_segment_ptr(); asm volatile("" : "+s"(p_)); p_; })
; __global__ void __launch_bounds__(NWAVES * 64, 2) hybrid_fwd(Args args) {
;     ...
;     {
;         KArgs args = KA();
;         LAS float* scr = (LAS float*)(lds + RING_OFF + wave * 16384);
;         const int gw = c * NWAVES + wave, NGW = G * NWAVES;
;         constexpr int I_A = 16 * (5120 / 32), I_B = 16 * (6144 / 32), I_S = 16 * 32;
;         constexpr int NITEMS = I_A + I_B + 6 * I_S;
;         for (int it = gw; it < NITEMS; it += NGW) {
;             int r = it;
;             if (r < I_A) { p0_transpose_item(args->w_in, IN_COLS, D, 5120, WinT, scr, r, lane); continue; } r -= I_A;
;             if (r < I_B) { p0_transpose_item(args->w_in + 5136, IN_COLS, D, 6144, WinT + (size_t)5120 * D, scr, r, lane); continue; } r -= I_B;
;             if (r < I_S) { p0_transpose_item(args->w_mem_k, D, D, D, WkT, scr, r, lane); continue; } r -= I_S;
;             if (r < I_S) { p0_transpose_item(args->w_mem_v, D, D, D, WvT, scr, r, lane); continue; } r -= I_S;
;             if (r < 3 * I_S) { const int nb = r / I_S; p0_transpose_item(args->w_branch + (size_t)nb * D * D, D, D, D, WBt + (size_t)nb * D * D, scr, r % I_S, lane); continue; } r -= 3 * I_S;
;             p0_transpose_item(args->w_out, D, D, D, WoT, scr, r, lane);
;         }
.LBB0_11:
	s_or_b64 exec, exec, s[4:5]
	s_bitcmp1_b32 s2, 6
	s_cselect_b32 s100, 0, 3
.Lp0_pre:
	s_lshr_b32 s6, s2, 6
	s_add_u32 s4, s18, 0x200000
	v_readlane_b32 s2, v255, 0
	s_addc_u32 s5, s19, 0
	s_mov_b64 s[20:21], s[0:1]
	s_lshl_b32 s2, s2, 3
	v_writelane_b32 v255, s2, 4
	s_add_i32 s14, s6, s2
	s_load_dword s2, s[0:1], 0xa8
	v_and_b32_e32 v7, 63, v236
	v_and_b32_e32 v6, 31, v236
	v_lshlrev_b32_e32 v9, 3, v236
	s_waitcnt lgkmcnt(0)
	s_lshl_b32 s12, s2, 3
	s_cmp_lg_u32 s100, 0
	s_cbranch_scc1 .Lp0_go
	s_mov_b32 s100, 1
	s_branch .Lp0_rms
.Lp0_go:
	s_cmpk_gt_i32 s14, 0x21ff
	s_cbranch_scc1 .LBB0_46
	v_and_b32_e32 v20, 56, v9
	v_mov_b32_e32 v5, 0
	v_lshlrev_b32_e32 v4, 1, v20
	v_lshl_add_u64 v[16:17], s[18:19], 0, v[4:5]
	s_mov_b64 s[8:9], 0x2300000
	s_add_u32 s2, s18, 0x1d00000
	v_lshl_add_u64 v[10:11], v[16:17], 0, s[8:9]
	s_mov_b64 s[8:9], 0x1b00000
	s_addc_u32 s3, s19, 0
	s_lshl_b32 s6, s6, 14
	v_lshrrev_b32_e32 v27, 3, v7
	v_lshl_add_u64 v[12:13], v[16:17], 0, s[8:9]
	s_mov_b64 s[8:9], 0x1900000
	s_add_i32 s6, s6, 0
	v_lshrrev_b32_e32 v2, 5, v7
	v_mul_u32_u24_e32 v1, 0x84, v20
	v_lshlrev_b32_e32 v3, 2, v27
	v_lshl_add_u64 v[14:15], v[16:17], 0, s[8:9]
	s_mov_b64 s[8:9], 0xc00000
	s_mov_b32 s7, 0
	v_lshl_add_u32 v8, v6, 2, s6
	s_movk_i32 s13, 0x84
	v_add3_u32 v28, s6, v1, v3
	v_or_b32_e32 v29, 8, v27
	v_or_b32_e32 v30, 16, v27
	v_or_b32_e32 v31, 24, v27
	v_lshl_add_u64 v[16:17], v[16:17], 0, s[8:9]
	v_lshl_add_u64 v[18:19], s[4:5], 0, v[4:5]
	v_mov_b32_e32 v1, v2
	s_movk_i32 s15, 0x7fff
	s_mov_b32 s16, 0xffff0000
	v_lshlrev_b32_e32 v20, 1, v20
	s_mov_b64 s[8:9], 0x5040
	s_mov_b32 s17, 0xb040
	v_lshlrev_b32_e32 v22, 2, v6
	s_mov_b32 s26, s14
	s_branch .LBB0_14

; #define GAS __attribute__((address_space(1)))
; __device__ __forceinline__ unsigned pk2(float lo, float hi) { return f2bf(lo) | (f2bf(hi) << 16); }
; template <class T_> __device__ __forceinline__ T_* as_global(T_* p) { return (T_*)(GAS T_*)p; }
; __device__ __forceinline__ void rms_rows4_to_bf16(const float* xrow, const float* g, bf16* orow, int lane) {
;     const GAS f32x4* xr = (const GAS f32x4*)xrow + lane; const GAS f32x4* gr = (const GAS f32x4*)g + lane;
;     f32x4 v[4][4]; float s[4] = {0.f, 0.f, 0.f, 0.f};
; #pragma unroll
;     for (int r = 0; r < 4; ++r)
; #pragma unroll
;         for (int j = 0; j < 4; ++j) v[r][j] = xr[r * (D / 4) + 64 * j];
; #pragma unroll
;     for (int r = 0; r < 4; ++r)
; #pragma unroll
;         for (int j = 0; j < 4; ++j) s[r] += (v[r][j].x * v[r][j].x + v[r][j].y * v[r][j].y) + (v[r][j].z * v[r][j].z + v[r][j].w * v[r][j].w);
; #pragma unroll
;     for (int r = 0; r < 4; ++r) { const float rs = 1.f / sqrtf(wave_sum(s[r], lane) * (1.f / D) + RMS_EPS);
;         GAS unsigned long long* o8 = (GAS unsigned long long*)(orow + (size_t)r * D) + lane;
; #pragma unroll
;         for (int j = 0; j < 4; ++j) { const f32x4 gg = gr[64 * j];
;             o8[64 * j] = (unsigned long long)pk2(v[r][j].x * rs * gg.x, v[r][j].y * rs * gg.y) | ((unsigned long long)pk2(v[r][j].z * rs * gg.z, v[r][j].w * rs * gg.w) << 32); } }
; __global__ void __launch_bounds__(NWAVES * 64, 2) hybrid_fwd(Args args) {
;     ...
;         { const float* xg0 = as_global(args->x); const float* gp0 = as_global(args->g_pre);
;           for (int m = 4 * gw; m < MTOK; m += 4 * NGW) rms_rows4_to_bf16(xg0 + (size_t)m * D, gp0, XN + (size_t)m * D, lane); }
.LBB0_57:
	s_or_b64 exec, exec, s[4:5]
	s_cmp_eq_u32 s100, 2
	s_cbranch_scc1 .LBB0_63
.Lp0_rms:
	s_cmpk_gt_i32 s14, 0x3fff
	v_lshlrev_b32_e32 v70, 4, v7
	v_lshlrev_b32_e32 v1, 2, v7
	v_lshlrev_b32_e32 v72, 3, v7
	s_cbranch_scc1 .LBB0_60
	s_load_dwordx2 s[2:3], s[20:21], 0x10
	s_load_dwordx2 s[4:5], s[20:21], 0x0
	v_mov_b32_e32 v71, 0
	s_lshl_b32 s22, s14, 2
	s_ashr_i32 s23, s22, 31
	s_waitcnt lgkmcnt(0)
	v_lshl_add_u64 v[74:75], s[2:3], 0, v[70:71]
	s_load_dword s2, s[0:1], 0xa8
	v_mov_b32_e32 v73, v71
	v_xor_b32_e32 v82, 4, v1
	v_xor_b32_e32 v83, 8, v1
	v_xor_b32_e32 v84, 16, v1
	s_waitcnt lgkmcnt(0)
	s_lshl_b32 s24, s2, 5
	s_lshl_b64 s[2:3], s[22:23], 12
	s_add_u32 s2, s4, s2
	s_addc_u32 s3, s5, s3
	s_ashr_i32 s25, s24, 31
	v_lshl_add_u64 v[76:77], s[2:3], 0, v[70:71]
	s_lshl_b64 s[26:27], s[24:25], 12
	s_lshl_b64 s[2:3], s[22:23], 11
	s_add_u32 s2, s18, s2
	s_addc_u32 s3, s19, s3
	v_lshl_add_u64 v[2:3], s[2:3], 0, v[72:73]
	s_mov_b64 s[2:3], 0x3c00000
	v_xor_b32_e32 v85, 32, v1
	v_xor_b32_e32 v86, 64, v1
	v_xor_b32_e32 v87, 0x80, v1
	v_lshl_add_u64 v[78:79], v[2:3], 0, s[2:3]
	s_lshl_b64 s[28:29], s[24:25], 11
	s_movk_i32 s2, 0x1000
	v_mov_b32_e32 v71, 0x358637bd
	s_mov_b32 s3, 0xf800000
	v_mov_b32_e32 v73, 0x260
	s_movk_i32 s13, 0x7fff
	s_mov_b32 s15, 0xffff0000

; __global__ void __launch_bounds__(NWAVES * 64, 2) hybrid_fwd(Args args) {
;     ...
;         for (int it = gw; it < NITEMS; it += NGW) {
;             int r = it;
;             if (r < I_A) { p0_transpose_item(args->w_in, IN_COLS, D, 5120, WinT, scr, r, lane); continue; } r -= I_A;
;             if (r < I_B) { p0_transpose_item(args->w_in + 5136, IN_COLS, D, 6144, WinT + (size_t)5120 * D, scr, r, lane); continue; } r -= I_B;
;             if (r < I_S) { p0_transpose_item(args->w_mem_k, D, D, D, WkT, scr, r, lane); continue; } r -= I_S;
;             if (r < I_S) { p0_transpose_item(args->w_mem_v, D, D, D, WvT, scr, r, lane); continue; } r -= I_S;
;             if (r < 3 * I_S) { const int nb = r / I_S; p0_transpose_item(args->w_branch + (size_t)nb * D * D, D, D, D, WBt + (size_t)nb * D * D, scr, r % I_S, lane); continue; } r -= 3 * I_S;
;             p0_transpose_item(args->w_out, D, D, D, WoT, scr, r, lane);
;         }
;         const int gt = c * (NWAVES * 64) + tid, NGT = G * NWAVES * 64;
;         for (int e = gt; e < 256 * 128; e += NGT) { const int row = e >> 7, k8 = (e & 127) * 8; v4u o = (v4u){0u, 0u, 0u, 0u};
;             if (row < 16) { const float* s = args->w_in + (size_t)k8 * IN_COLS + 5120 + row;
;                 o.x = pk2(s[0], s[IN_COLS]); o.y = pk2(s[2 * IN_COLS], s[3 * IN_COLS]); o.z = pk2(s[4 * IN_COLS], s[5 * IN_COLS]); o.w = pk2(s[6 * IN_COLS], s[7 * IN_COLS]); }
;             *(v4u*)(WinT + (size_t)(NZC + row) * D + k8) = o; }
;         for (int e = gt; e < 16 * 2 * 2 * 4 * 64; e += NGT) { const int ln = e & 63, ks = (e >> 6) & 3, rb = (e >> 8) & 1, mat = (e >> 9) & 1, gg = e >> 10;
;             const float* Wm = (mat ? args->w_lru_i : args->w_lru_r) + (size_t)gg * 64 * 64; const int j = 32 * rb + (ln & 31), hh = ln >> 5;
;             float f[8];
; #pragma unroll
;             for (int q = 0; q < 8; ++q) { const int k = 8 * (2 * ks + (q >> 2)) + 4 * hh + (q & 3); f[q] = Wm[k * 64 + j]; }
;             v4u o; o.x = pk2(f[0], f[1]); o.y = pk2(f[2], f[3]); o.z = pk2(f[4], f[5]); o.w = pk2(f[6], f[7]);
;             *(v4u*)((bf16*)(ws + WS_WRF) + (size_t)e * 8) = o; }
;         for (int e = gt; e < D; e += NGT) { const float x = -args->lru_lambda[e]; const float sp = fmaxf(x, 0.f) + log1pf(expf(-fabsf(x))); ((float*)(ws + WS_COEF))[e] = -8.f * sp * LOG2E; }
.LBB0_63:
	s_cmp_eq_u32 s100, 1
	s_cbranch_scc0 .Lp0_end
	s_mov_b32 s100, 2
	v_readfirstlane_b32 s2, v236
	s_branch .Lp0_pre

; template<int THRL> __device__ __forceinline__ void attn_unit(int b,int h,int qb,const bf16*Q,const bf16*__restrict__ K,const bf16*__restrict__ V,bf16*O,const bf16*GF,const float*CBh,const unsigned*KN,const unsigned*QN,char*shm){
;     ...
;   { const int n4=(q0+QB)>>2; f32x4*dst=(f32x4*)(shm+LDS_BIAS); const f32x4*src=(const f32x4*)CBh;
;     for(int i=tid;i<n4;i+=NW*64)dst[i]=src[i]; }
;   bf16x8 qr[4];
;   #pragma unroll
;   for(int d0=0;d0<4;++d0)qr[d0]=*reinterpret_cast<const bf16x8*>(&Qw[(long)r32*DM+d0*16+hi*8]);
;   float umin;
;   { const bf16*Kd=K+(rowbase+q0+wid*QBLK)*DM+h*D; float ds=0.f,qq=0.f;
;     #pragma unroll
;     for(int d0=0;d0<4;++d0){ const bf16x8 kk=*reinterpret_cast<const bf16x8*>(&Kd[(long)r32*DM+d0*16+hi*8]);
;       #pragma unroll
;       for(int e=0;e<8;++e){ const float qf=__builtin_bit_cast(float,(unsigned)(unsigned short)qr[d0][e]<<16); ds+=qf*__builtin_bit_cast(float,(unsigned)(unsigned short)kk[e]<<16); qq+=qf*qf; } }
.LBB0_561:
	s_or_b64 exec, exec, s[6:7]
	s_or_b32 s2, s51, s25
	s_lshl_b64 s[8:9], s[18:19], 16
	s_lshl_b32 s18, s2, 13
	s_lshl_b64 s[6:7], s[18:19], 2
	s_add_u32 s44, s77, s6
	s_addc_u32 s45, s33, s7
	s_lshl_b32 s18, s2, 1
	s_lshl_b64 s[6:7], s[18:19], 2
	s_add_u32 s6, s54, s6
	s_addc_u32 s7, s55, s7
	s_lshl_b32 s14, s14, 13
	s_sub_i32 s2, 0x1f00, s15
	s_lshl_b32 s41, s67, 5
	s_add_i32 s14, s2, s14
	s_ashr_i32 s15, s41, 31
	s_add_u32 s42, s41, s14
	s_addc_u32 s43, s15, 0
	s_lshl_b64 s[52:53], s[42:43], 11
	s_add_u32 s14, s56, s52
	s_addc_u32 s15, s57, s53
	s_add_u32 s14, s14, s66
	s_addc_u32 s15, s15, 0
	s_and_b32 s18, s46, 0x3fffffc0
	s_lshl_b32 s18, s18, 2
	s_add_i32 s50, s18, 0
	s_add_u32 s18, s58, s52
	v_and_b32_e32 v190, 31, v34
	s_addc_u32 s47, s59, s53
	v_lshrrev_b32_e32 v191, 5, v188
	v_lshlrev_b32_e32 v0, 11, v190
	s_add_u32 s46, s18, s66
	v_lshl_or_b32 v0, v191, 4, v0
	s_addc_u32 s47, s47, 0
	global_load_dwordx4 v[126:129], v0, s[14:15]
	global_load_dwordx4 v[122:125], v0, s[14:15] offset:32
	global_load_dwordx4 v[118:121], v0, s[14:15] offset:64
	global_load_dwordx4 v[114:117], v0, s[14:15] offset:96
	global_load_dwordx4 v[2:5], v0, s[46:47]
	s_add_i32 s2, s41, s2
	global_load_dwordx4 v[58:61], v0, s[46:47] offset:32
	global_load_dwordx4 v[62:65], v0, s[46:47] offset:64
	global_load_dwordx4 v[66:69], v0, s[46:47] offset:96
	global_load_dwordx2 v[70:71], v1, s[6:7]
	v_or_b32_e32 v74, s2, v190
	v_ashrrev_i32_e32 v75, 31, v74
	v_lshl_add_u64 v[74:75], v[74:75], 2, s[44:45]
	global_load_dword v72, v[74:75], off
	s_waitcnt vmcnt(9)
	v_cmp_gt_i32_e32 vcc, v56, v34
	s_and_b64 exec, exec, vcc
	ds_write_b128 v52, v[36:39]
	v_add_u32_e32 v53, 0x200, v34
	v_cmp_gt_i32_e32 vcc, v56, v53
	s_and_b64 exec, exec, vcc
	ds_write_b128 v52, v[40:43] offset:8192
	v_add_u32_e32 v53, 0x400, v34
	v_cmp_gt_i32_e32 vcc, v56, v53
	s_and_b64 exec, exec, vcc
	ds_write_b128 v52, v[44:47] offset:16384
	v_add_u32_e32 v53, 0x600, v34
	v_cmp_gt_i32_e32 vcc, v56, v53
	s_and_b64 exec, exec, vcc
	ds_write_b128 v52, v[48:51] offset:24576
	s_mov_b64 exec, -1
	v_lshlrev_b32_e32 v6, 16, v126
	v_and_b32_e32 v8, 0xffff0000, v126
	s_waitcnt vmcnt(5)
	v_lshlrev_b32_e32 v7, 16, v2
	v_fma_f32 v7, v6, v7, 0
	v_and_b32_e32 v2, 0xffff0000, v2
	v_fmac_f32_e32 v7, v8, v2
	v_mul_f32_e32 v8, v8, v8
	v_fmac_f32_e32 v8, v6, v6
	v_lshlrev_b32_e32 v2, 16, v127
	v_lshlrev_b32_e32 v6, 16, v3
	v_fmac_f32_e32 v7, v2, v6
	v_fmac_f32_e32 v8, v2, v2
	v_and_b32_e32 v2, 0xffff0000, v127
	v_and_b32_e32 v3, 0xffff0000, v3
	v_fmac_f32_e32 v7, v2, v3
	v_fmac_f32_e32 v8, v2, v2
	v_lshlrev_b32_e32 v2, 16, v128
	v_lshlrev_b32_e32 v3, 16, v4
	v_fmac_f32_e32 v7, v2, v3
	v_fmac_f32_e32 v8, v2, v2
	v_and_b32_e32 v2, 0xffff0000, v128
	v_and_b32_e32 v3, 0xffff0000, v4
	v_fmac_f32_e32 v7, v2, v3
	v_fmac_f32_e32 v8, v2, v2
	v_lshlrev_b32_e32 v2, 16, v129
	v_lshlrev_b32_e32 v3, 16, v5
	v_fmac_f32_e32 v7, v2, v3
	v_fmac_f32_e32 v8, v2, v2
	v_and_b32_e32 v2, 0xffff0000, v129
	v_and_b32_e32 v3, 0xffff0000, v5
	v_fmac_f32_e32 v7, v2, v3
	v_fmac_f32_e32 v8, v2, v2
	s_waitcnt vmcnt(4)
	v_mov_b32_e32 v2, v58
	v_mov_b32_e32 v3, v59
	v_mov_b32_e32 v4, v60
	v_mov_b32_e32 v5, v61
	v_lshlrev_b32_e32 v6, 16, v122
	v_fmac_f32_e32 v8, v6, v6
	v_lshlrev_b32_e32 v9, 16, v2
	v_fmac_f32_e32 v7, v6, v9
	v_and_b32_e32 v6, 0xffff0000, v122
	v_and_b32_e32 v2, 0xffff0000, v2
	v_fmac_f32_e32 v7, v6, v2
	v_fmac_f32_e32 v8, v6, v6
	v_lshlrev_b32_e32 v2, 16, v123
	v_lshlrev_b32_e32 v6, 16, v3
	v_fmac_f32_e32 v7, v2, v6
	v_fmac_f32_e32 v8, v2, v2
	v_and_b32_e32 v2, 0xffff0000, v123
	v_and_b32_e32 v3, 0xffff0000, v3
	v_fmac_f32_e32 v7, v2, v3
	v_fmac_f32_e32 v8, v2, v2
	v_lshlrev_b32_e32 v2, 16, v124
	v_lshlrev_b32_e32 v3, 16, v4
	v_fmac_f32_e32 v7, v2, v3
	v_fmac_f32_e32 v8, v2, v2
	v_and_b32_e32 v2, 0xffff0000, v124
	v_and_b32_e32 v3, 0xffff0000, v4
	v_fmac_f32_e32 v7, v2, v3
	v_fmac_f32_e32 v8, v2, v2
	v_lshlrev_b32_e32 v2, 16, v125
	v_lshlrev_b32_e32 v3, 16, v5
	v_fmac_f32_e32 v7, v2, v3
	v_fmac_f32_e32 v8, v2, v2
	v_and_b32_e32 v2, 0xffff0000, v125
	v_and_b32_e32 v3, 0xffff0000, v5
	v_fmac_f32_e32 v7, v2, v3
	v_fmac_f32_e32 v8, v2, v2
	s_waitcnt vmcnt(3)
; template<int THRL> __device__ __forceinline__ void attn_unit(int b,int h,int qb,const bf16*Q,const bf16*__restrict__ K,const bf16*__restrict__ V,bf16*O,const bf16*GF,const float*CBh,const unsigned*KN,const unsigned*QN,char*shm){
;     ...
;     for(int d0=0;d0<4;++d0){ const bf16x8 kk=*reinterpret_cast<const bf16x8*>(&Kd[(long)r32*DM+d0*16+hi*8]);
;       #pragma unroll
;       for(int e=0;e<8;++e){ const float qf=__builtin_bit_cast(float,(unsigned)(unsigned short)qr[d0][e]<<16); ds+=qf*__builtin_bit_cast(float,(unsigned)(unsigned short)kk[e]<<16); qq+=qf*qf; } }
;     { auto rr=__builtin_amdgcn_permlane32_swap(__float_as_uint(ds),__float_as_uint(ds),false,false); ds=__uint_as_float(rr[0])+__uint_as_float(rr[1]); }
;     { auto rr=__builtin_amdgcn_permlane32_swap(__float_as_uint(qq),__float_as_uint(qq),false,false); qq=__uint_as_float(rr[0])+__uint_as_float(rr[1]); }
;     const float kmx=sqrtf(__uint_as_float(KN[0])+__uint_as_float(KN[1]));
;     float v=ds+CBh[q0+wid*QBLK+r32]-sqrtf(qq)*kmx*1.001f;
;     #pragma unroll
;     for(int m=1;m<32;m<<=1)v=fminf(v,__builtin_bit_cast(float,__builtin_amdgcn_ds_bpermute((lane^m)<<2,__builtin_bit_cast(int,v))));
;     float*wmin=(float*)(shm+LDS_WS);
;     if(lane==0)wmin[wid*64]=v;
	v_mov_b32_e32 v2, v62
	v_mov_b32_e32 v3, v63
	v_mov_b32_e32 v4, v64
	v_mov_b32_e32 v5, v65
	v_lshlrev_b32_e32 v6, 16, v118
	v_fmac_f32_e32 v8, v6, v6
	v_lshlrev_b32_e32 v9, 16, v2
	v_fmac_f32_e32 v7, v6, v9
	v_and_b32_e32 v6, 0xffff0000, v118
	v_and_b32_e32 v2, 0xffff0000, v2
	v_fmac_f32_e32 v7, v6, v2
	v_fmac_f32_e32 v8, v6, v6
	v_lshlrev_b32_e32 v2, 16, v119
	v_lshlrev_b32_e32 v6, 16, v3
	v_fmac_f32_e32 v7, v2, v6
	v_fmac_f32_e32 v8, v2, v2
	v_and_b32_e32 v2, 0xffff0000, v119
	v_and_b32_e32 v3, 0xffff0000, v3
	v_fmac_f32_e32 v7, v2, v3
	v_fmac_f32_e32 v8, v2, v2
	v_lshlrev_b32_e32 v2, 16, v120
	v_lshlrev_b32_e32 v3, 16, v4
	v_fmac_f32_e32 v7, v2, v3
	v_fmac_f32_e32 v8, v2, v2
	v_and_b32_e32 v2, 0xffff0000, v120
	v_and_b32_e32 v3, 0xffff0000, v4
	v_fmac_f32_e32 v7, v2, v3
	v_fmac_f32_e32 v8, v2, v2
	v_lshlrev_b32_e32 v2, 16, v121
	v_lshlrev_b32_e32 v3, 16, v5
	v_fmac_f32_e32 v7, v2, v3
	v_fmac_f32_e32 v8, v2, v2
	v_and_b32_e32 v2, 0xffff0000, v121
	v_and_b32_e32 v3, 0xffff0000, v5
	v_fmac_f32_e32 v7, v2, v3
	v_fmac_f32_e32 v8, v2, v2
	s_waitcnt vmcnt(2)
	v_mov_b32_e32 v2, v66
	v_mov_b32_e32 v3, v67
	v_mov_b32_e32 v4, v68
	v_mov_b32_e32 v5, v69
	v_lshlrev_b32_e32 v6, 16, v114
	v_fmac_f32_e32 v8, v6, v6
	v_lshlrev_b32_e32 v0, 16, v2
	v_fmac_f32_e32 v7, v6, v0
	v_and_b32_e32 v0, 0xffff0000, v114
	v_and_b32_e32 v2, 0xffff0000, v2
	v_fmac_f32_e32 v7, v0, v2
	v_fmac_f32_e32 v8, v0, v0
	v_lshlrev_b32_e32 v0, 16, v115
	v_lshlrev_b32_e32 v2, 16, v3
	v_fmac_f32_e32 v7, v0, v2
	v_fmac_f32_e32 v8, v0, v0
	v_and_b32_e32 v0, 0xffff0000, v115
	v_and_b32_e32 v2, 0xffff0000, v3
	v_fmac_f32_e32 v7, v0, v2
	v_fmac_f32_e32 v8, v0, v0
	v_lshlrev_b32_e32 v0, 16, v116
	v_lshlrev_b32_e32 v2, 16, v4
	v_fmac_f32_e32 v7, v0, v2
	v_fmac_f32_e32 v8, v0, v0
	v_and_b32_e32 v0, 0xffff0000, v116
	v_and_b32_e32 v2, 0xffff0000, v4
	v_fmac_f32_e32 v7, v0, v2
	v_fmac_f32_e32 v8, v0, v0
	v_lshlrev_b32_e32 v0, 16, v117
	v_lshlrev_b32_e32 v2, 16, v5
	v_fmac_f32_e32 v7, v0, v2
	v_fmac_f32_e32 v8, v0, v0
	v_and_b32_e32 v0, 0xffff0000, v117
	v_and_b32_e32 v2, 0xffff0000, v5
	v_fmac_f32_e32 v7, v0, v2
	s_waitcnt vmcnt(1)
	v_mov_b32_e32 v2, v70
	v_mov_b32_e32 v3, v71
	v_fmac_f32_e32 v8, v0, v0
	v_mov_b32_e32 v0, v7
	s_nop 1
	v_permlane32_swap_b32_e32 v7, v0
	v_add_f32_e32 v4, v7, v0
	v_mov_b32_e32 v0, v8
	s_nop 1
	v_permlane32_swap_b32_e32 v8, v0
	v_add_f32_e32 v0, v8, v0
	s_waitcnt vmcnt(1)
	v_add_f32_e32 v2, v2, v3
	v_cmp_gt_f32_e32 vcc, s3, v2
	v_mul_f32_e32 v3, 0x4f800000, v2
	s_nop 0
	v_cndmask_b32_e32 v2, v2, v3, vcc
	v_sqrt_f32_e32 v3, v2
	s_nop 0
	v_add_u32_e32 v5, -1, v3
	v_fma_f32 v6, -v5, v3, v2
	v_cmp_ge_f32_e64 s[6:7], 0, v6
	v_add_u32_e32 v6, 1, v3
	s_nop 0
	v_cndmask_b32_e64 v5, v3, v5, s[6:7]
	v_fma_f32 v3, -v6, v3, v2
	v_cmp_lt_f32_e64 s[6:7], 0, v3
	s_nop 1
	v_cndmask_b32_e64 v3, v5, v6, s[6:7]
	v_mul_f32_e32 v5, 0x37800000, v3
	v_cndmask_b32_e32 v3, v3, v5, vcc
	v_cmp_class_f32_e32 vcc, v2, v231
	s_nop 1
	v_cndmask_b32_e32 v5, v3, v2, vcc
	v_or_b32_e32 v2, s2, v190
	v_ashrrev_i32_e32 v3, 31, v2
	v_lshl_add_u64 v[2:3], v[2:3], 2, s[44:45]
	s_waitcnt vmcnt(0)
	v_mov_b32_e32 v2, v72
	v_cmp_gt_f32_e32 vcc, s3, v0
	v_mul_f32_e32 v3, 0x4f800000, v0
	s_waitcnt vmcnt(0)
	v_add_f32_e32 v2, v4, v2
	v_cndmask_b32_e32 v0, v0, v3, vcc
	v_sqrt_f32_e32 v3, v0
	s_nop 0
	v_add_u32_e32 v4, -1, v3
	v_fma_f32 v6, -v4, v3, v0
	v_cmp_ge_f32_e64 s[6:7], 0, v6
	v_add_u32_e32 v6, 1, v3
	s_nop 0
	v_cndmask_b32_e64 v4, v3, v4, s[6:7]
	v_fma_f32 v3, -v6, v3, v0
	v_cmp_lt_f32_e64 s[6:7], 0, v3
	s_nop 1
	v_cndmask_b32_e64 v3, v4, v6, s[6:7]
	v_mul_f32_e32 v4, 0x37800000, v3
	v_cndmask_b32_e32 v3, v3, v4, vcc
	v_cmp_class_f32_e32 vcc, v0, v231
	s_nop 1
	v_cndmask_b32_e32 v0, v3, v0, vcc
	v_mul_f32_e32 v0, v0, v5
	v_lshlrev_b32_e32 v3, 2, v188
	v_fmac_f32_e32 v2, 0xbf8020c5, v0
	v_mul_f32_e32 v227, 0x3f8020c5, v0
	v_xor_b32_e32 v0, 4, v3
	ds_bpermute_b32 v0, v0, v2
	v_cmp_eq_u32_e32 vcc, 0, v188
	s_waitcnt lgkmcnt(0)
	v_max_f32_e32 v0, v0, v0
	v_min_f32_e32 v0, v2, v0
	v_xor_b32_e32 v2, 8, v3
	ds_bpermute_b32 v2, v2, v0
	s_waitcnt lgkmcnt(0)
	v_max_f32_e32 v2, v2, v2
	v_min_f32_e32 v0, v0, v2
	v_xor_b32_e32 v2, 16, v3
	ds_bpermute_b32 v2, v2, v0
	s_waitcnt lgkmcnt(0)
	v_max_f32_e32 v2, v2, v2
	v_min_f32_e32 v0, v0, v2
	v_xor_b32_e32 v2, 32, v3
	ds_bpermute_b32 v2, v2, v0
	s_waitcnt lgkmcnt(0)
	v_max_f32_e32 v2, v2, v2
	v_min_f32_e32 v0, v0, v2
	v_xor_b32_e32 v2, 64, v3
	ds_bpermute_b32 v2, v2, v0
	s_and_saveexec_b64 s[6:7], vcc
	s_cbranch_execz .LBB0_563
	s_waitcnt lgkmcnt(0)
	v_max_f32_e32 v2, v2, v2
	v_max_f32_e32 v0, v0, v0
	v_min_f32_e32 v0, v0, v2
	v_mov_b32_e32 v2, s50
	ds_write_b32 v2, v0 offset:49152

; #define WAIT_BAR(N) asm volatile("s_waitcnt vmcnt(" #N ") lgkmcnt(0)\n\ts_barrier":::"memory")
;   #define RESC() do{ if(resc){ asm volatile("s_waitcnt lgkmcnt(0)":::"memory"); \
;       _Pragma("unroll") for(int d_=0;d_<2;++d_) _Pragma("unroll") for(int r=0;r<16;++r)o[d_][r]*=wsf[crow(r,hi)]; } }while(0)
;   #define ROT() do{sl_prev=sl_cur;sl_cur=sl_next;sl_next=(sl_next==(NSLOT-1)*SLOTB)?0:sl_next+SLOTB;}while(0)
; template<int THRL> __device__ __forceinline__ void attn_unit(int b,int h,int qb,const bf16*Q,const bf16*__restrict__ K,const bf16*__restrict__ V,bf16*O,const bf16*GF,const float*CBh,const unsigned*KN,const unsigned*QN,char*shm){
;     ...
;   for(;t+5<NT;t+=2){
;     STEP(pB0,pB1,pA0,pA1,t,true,true,true);     WAIT_BAR(2); RESC(); ROT();
;     STEP(pA0,pA1,pB0,pB1,t+1,true,true,true);   WAIT_BAR(2); RESC(); ROT();
.LBB0_617:
	s_add_i32 s2, s72, 5
	s_cmp_ge_i32 s2, s41
	s_cbranch_scc1 .LBB0_633
	s_add_i32 s51, s71, -4
	v_cmp_gt_u32_e64 s[6:7], 32, v188
	s_lshl_b32 s100, s68, 8
	s_add_i32 s100, s100, s89
	s_add_i32 s100, s100, 0xfffffbfc
	v_mov_b32_e32 v228, s100
	ds_read_b32 v228, v228
	v_sub_f32_e32 v229, v227, v223
	s_mov_b32 s100, 0
	s_waitcnt lgkmcnt(0)
	v_add_f32_e32 v229, v229, v228
	v_cmp_lt_f32_e32 vcc, s92, v229
	s_cmp_lg_u64 vcc, 0
	s_cbranch_scc1 .Lmx_noflag
	s_mov_b32 s100, 1
.Lmx_noflag:
.LBB0_619:
	s_add_i32 s2, s68, s72
	s_add_i32 s8, s71, s72
	s_cmp_lt_u32 s72, 4
	s_cselect_b32 s9, s2, s8
	v_lshl_add_u32 v67, s9, 8, v224
	v_add_u32_e32 v67, 0xfffffc00, v67
	ds_read_b128 v[68:71], v67
	ds_read_b128 v[72:75], v67 offset:32
	ds_read_b128 v[76:79], v67 offset:64
	ds_read_b128 v[80:83], v67 offset:96
	ds_read_b128 v[100:103], v67 offset:128
	ds_read_b128 v[104:107], v67 offset:160
	ds_read_b128 v[108:111], v67 offset:192
	ds_read_b128 v[178:181], v67 offset:224
	v_add_u32_e32 v0, s74, v222
	s_waitcnt lgkmcnt(4)
	v_sub_f32_e32 v99, v83, v223
	v_sub_f32_e32 v98, v82, v223
	v_sub_f32_e32 v97, v81, v223
	v_sub_f32_e32 v96, v80, v223
	v_sub_f32_e32 v95, v79, v223
	v_sub_f32_e32 v94, v78, v223
	v_sub_f32_e32 v93, v77, v223
	v_sub_f32_e32 v92, v76, v223
	v_sub_f32_e32 v91, v75, v223
	v_sub_f32_e32 v90, v74, v223
	v_sub_f32_e32 v89, v73, v223
	v_sub_f32_e32 v88, v72, v223
	v_sub_f32_e32 v87, v71, v223
	v_sub_f32_e32 v86, v70, v223
	v_sub_f32_e32 v85, v69, v223
	v_sub_f32_e32 v84, v68, v223
	s_waitcnt lgkmcnt(0)
	v_sub_f32_e32 v83, v181, v223
	v_sub_f32_e32 v82, v180, v223
	v_sub_f32_e32 v81, v179, v223
	v_sub_f32_e32 v80, v178, v223
	v_sub_f32_e32 v79, v111, v223
	v_sub_f32_e32 v78, v110, v223
	v_sub_f32_e32 v77, v109, v223
	v_sub_f32_e32 v76, v108, v223
	v_sub_f32_e32 v75, v107, v223
	v_sub_f32_e32 v74, v106, v223
	v_sub_f32_e32 v73, v105, v223
	v_sub_f32_e32 v72, v104, v223
	v_sub_f32_e32 v71, v103, v223
	v_sub_f32_e32 v70, v102, v223
	v_sub_f32_e32 v69, v101, v223
	v_sub_f32_e32 v68, v100, v223
	ds_read_b64_tr_b16 v[100:101], v0 offset:24576
	ds_read_b64_tr_b16 v[102:103], v0 offset:25088
	v_mfma_f32_32x32x16_bf16 v[84:99], v[174:177], v[126:129], v[84:99]
	v_add_f32_e32 v67, v50, v51
	v_add_f32_e32 v67, v52, v67
	v_add_f32_e32 v67, v53, v67
	v_add_f32_e32 v67, v54, v67
	v_add_f32_e32 v67, v55, v67
	v_cvt_pk_bf16_f32 v142, v50, v51
	v_cvt_pk_bf16_f32 v143, v52, v53
	ds_read_b64_tr_b16 v[50:51], v0 offset:28672
	ds_read_b64_tr_b16 v[52:53], v0 offset:29184
	v_mfma_f32_32x32x16_bf16 v[68:83], v[170:173], v[126:129], v[68:83]
	v_add_f32_e32 v67, v56, v67
	v_add_f32_e32 v67, v57, v67
	v_add_f32_e32 v67, v58, v67
	v_add_f32_e32 v67, v59, v67
	v_cvt_pk_bf16_f32 v144, v54, v55
	v_cvt_pk_bf16_f32 v145, v56, v57
	ds_read_b64_tr_b16 v[54:55], v0 offset:25600
	ds_read_b64_tr_b16 v[56:57], v0 offset:26112
	v_mfma_f32_32x32x16_bf16 v[84:99], v[166:169], v[122:125], v[84:99]
	v_add_f32_e32 v67, v60, v67
	v_add_f32_e32 v67, v61, v67
	v_add_f32_e32 v67, v62, v67
	v_add_f32_e32 v67, v63, v67
	v_cvt_pk_bf16_f32 v138, v58, v59
	v_cvt_pk_bf16_f32 v139, v60, v61
	ds_read_b64_tr_b16 v[58:59], v0 offset:29696
	ds_read_b64_tr_b16 v[60:61], v0 offset:30208
	v_mfma_f32_32x32x16_bf16 v[68:83], v[162:165], v[122:125], v[68:83]
	v_add_f32_e32 v67, v64, v67
	v_add_f32_e32 v67, v65, v67
	v_add_f32_e32 v67, v34, v67
	v_add_f32_e32 v67, v35, v67
	v_cvt_pk_bf16_f32 v140, v62, v63
	v_cvt_pk_bf16_f32 v141, v64, v65
	ds_read_b64_tr_b16 v[62:63], v0 offset:26624
	ds_read_b64_tr_b16 v[64:65], v0 offset:27136
	v_mfma_f32_32x32x16_bf16 v[84:99], v[158:161], v[118:121], v[84:99]
	v_add_f32_e32 v67, v36, v67
	v_add_f32_e32 v67, v37, v67
	v_add_f32_e32 v67, v38, v67
	v_add_f32_e32 v67, v39, v67
	v_cvt_pk_bf16_f32 v134, v34, v35
	v_cvt_pk_bf16_f32 v135, v36, v37
	ds_read_b64_tr_b16 v[34:35], v0 offset:30720
	ds_read_b64_tr_b16 v[36:37], v0 offset:31232
	v_mfma_f32_32x32x16_bf16 v[68:83], v[154:157], v[118:121], v[68:83]
	v_add_f32_e32 v67, v40, v67
	v_add_f32_e32 v67, v41, v67
	v_add_f32_e32 v67, v42, v67
	v_add_f32_e32 v67, v43, v67
	v_cvt_pk_bf16_f32 v136, v38, v39
	v_cvt_pk_bf16_f32 v137, v40, v41
	ds_read_b64_tr_b16 v[38:39], v0 offset:27648
	ds_read_b64_tr_b16 v[40:41], v0 offset:28160
	v_mfma_f32_32x32x16_bf16 v[84:99], v[150:153], v[114:117], v[84:99]
	v_add_f32_e32 v67, v44, v67
	v_add_f32_e32 v67, v45, v67
	v_add_f32_e32 v67, v46, v67
	v_add_f32_e32 v67, v47, v67
	v_cvt_pk_bf16_f32 v130, v42, v43
	v_cvt_pk_bf16_f32 v131, v44, v45
	ds_read_b64_tr_b16 v[42:43], v0 offset:31744
	ds_read_b64_tr_b16 v[44:45], v0 offset:32256
	v_mfma_f32_32x32x16_bf16 v[68:83], v[146:149], v[114:117], v[68:83]
	v_add_f32_e32 v0, v48, v67
	v_add_f32_e32 v0, v49, v0
	v_add_f32_e32 v0, 0, v0
	v_cvt_pk_bf16_f32 v132, v46, v47
	v_cvt_pk_bf16_f32 v133, v48, v49
	s_add_i32 s44, s8, -1
	s_ashr_i32 s45, s44, 31
	s_lshl_b64 s[44:45], s[44:45], 17
	s_add_i32 s9, s73, s69
	s_cmp_lt_u32 s72, 3
	v_lshl_add_u64 v[46:47], v[182:183], 0, s[44:45]
	s_mov_b32 s18, m0
	s_mov_b32 m0, s9
	s_nop 0
	global_load_lds_dwordx4 v[46:47], off
	s_mov_b32 m0, s18
	s_cselect_b32 s9, s40, s51
	s_add_i32 s9, s9, s72
	s_add_i32 s44, s9, 1
	s_ashr_i32 s45, s44, 31
	s_lshl_b64 s[46:47], s[44:45], 17
	v_lshl_add_u64 v[46:47], v[184:185], 0, s[46:47]
	s_add_i32 s9, s50, s70
	s_mov_b32 s18, m0
	s_mov_b32 m0, s9
	s_nop 0
	global_load_lds_dwordx4 v[46:47], off
	s_mov_b32 m0, s18
	s_cmp_lg_u32 s100, 0
	s_cbranch_scc0 .Lmx_full0
	v_add_f32_e32 v0, v66, v0
	s_mov_b64 s[46:47], 0
	s_branch .LBB0_620
.Lmx_full0:
	v_max_f32_e32 v46, v85, v85
	v_max_f32_e32 v47, v84, v84
	v_max_f32_e32 v46, v47, v46
	v_max3_f32 v47, v86, v87, v69
	v_max3_f32 v46, v46, v68, v70
	v_max3_f32 v46, v46, v71, v88
	v_max3_f32 v47, v47, v90, v91
	v_max3_f32 v46, v46, v89, v72
	v_max3_f32 v47, v47, v74, v75
	v_max3_f32 v46, v46, v73, v92
	v_max3_f32 v47, v47, v94, v95
	v_max3_f32 v46, v46, v93, v76
	v_max3_f32 v47, v47, v78, v79
	v_max3_f32 v46, v46, v77, v96
	v_max3_f32 v47, v47, v98, v99
	v_max3_f32 v46, v46, v97, v80
	v_max3_f32 v47, v47, v82, v83
	v_max3_f32 v46, v46, v81, v47
	v_mov_b32_e32 v47, v46
	s_nop 1
	v_permlane32_swap_b32_e32 v46, v47
	v_max_f32_e32 v47, v47, v47
	v_max_f32_e32 v46, v46, v46
	v_max_f32_e32 v46, v46, v47
	v_cmp_lt_f32_e32 vcc, s92, v46
	s_cmp_lg_u64 vcc, 0
	v_add_f32_e32 v0, v66, v0
	s_cselect_b64 s[46:47], -1, 0
	s_cbranch_vccnz .LBB0_627

; #define WAIT_BAR(N) asm volatile("s_waitcnt vmcnt(" #N ") lgkmcnt(0)\n\ts_barrier":::"memory")
;   #define RESC() do{ if(resc){ asm volatile("s_waitcnt lgkmcnt(0)":::"memory"); \
;       _Pragma("unroll") for(int d_=0;d_<2;++d_) _Pragma("unroll") for(int r=0;r<16;++r)o[d_][r]*=wsf[crow(r,hi)]; } }while(0)
;   #define ROT() do{sl_prev=sl_cur;sl_cur=sl_next;sl_next=(sl_next==(NSLOT-1)*SLOTB)?0:sl_next+SLOTB;}while(0)
; template<int THRL> __device__ __forceinline__ void attn_unit(int b,int h,int qb,const bf16*Q,const bf16*__restrict__ K,const bf16*__restrict__ V,bf16*O,const bf16*GF,const float*CBh,const unsigned*KN,const unsigned*QN,char*shm){
;     ...
;   for(;t+5<NT;t+=2){
;     STEP(pB0,pB1,pA0,pA1,t,true,true,true);     WAIT_BAR(2); RESC(); ROT();
;     STEP(pA0,pA1,pB0,pB1,t+1,true,true,true);   WAIT_BAR(2); RESC(); ROT();
.LBB0_622:
	s_add_i32 s9, s50, 0x2000
	s_cmpk_lg_i32 s50, 0x4000
	s_cselect_b32 s18, s9, 0
	v_lshl_add_u32 v50, s44, 8, v224
	ds_read_b128 v[34:37], v50
	ds_read_b128 v[38:41], v50 offset:32
	ds_read_b128 v[42:45], v50 offset:64
	ds_read_b128 v[46:49], v50 offset:96
	ds_read_b128 v[158:161], v50 offset:128
	ds_read_b128 v[170:173], v50 offset:160
	ds_read_b128 v[174:177], v50 offset:192
	ds_read_b128 v[178:181], v50 offset:224
	v_add_u32_e32 v66, s73, v222
	s_waitcnt lgkmcnt(4)
	v_sub_f32_e32 v65, v49, v223
	v_sub_f32_e32 v64, v48, v223
	v_sub_f32_e32 v63, v47, v223
	v_sub_f32_e32 v62, v46, v223
	v_sub_f32_e32 v61, v45, v223
	v_sub_f32_e32 v60, v44, v223
	v_sub_f32_e32 v59, v43, v223
	v_sub_f32_e32 v58, v42, v223
	v_sub_f32_e32 v57, v41, v223
	v_sub_f32_e32 v56, v40, v223
	v_sub_f32_e32 v55, v39, v223
	v_sub_f32_e32 v54, v38, v223
	v_sub_f32_e32 v53, v37, v223
	v_sub_f32_e32 v52, v36, v223
	v_sub_f32_e32 v51, v35, v223
	v_sub_f32_e32 v50, v34, v223
	s_waitcnt lgkmcnt(0)
	v_sub_f32_e32 v49, v181, v223
	v_sub_f32_e32 v48, v180, v223
	v_sub_f32_e32 v47, v179, v223
	v_sub_f32_e32 v46, v178, v223
	v_sub_f32_e32 v45, v177, v223
	v_sub_f32_e32 v44, v176, v223
	v_sub_f32_e32 v43, v175, v223
	v_sub_f32_e32 v42, v174, v223
	v_sub_f32_e32 v41, v173, v223
	v_sub_f32_e32 v40, v172, v223
	v_sub_f32_e32 v39, v171, v223
	v_sub_f32_e32 v38, v170, v223
	v_sub_f32_e32 v37, v161, v223
	v_sub_f32_e32 v36, v160, v223
	v_sub_f32_e32 v35, v159, v223
	v_sub_f32_e32 v34, v158, v223
	ds_read_b64_tr_b16 v[158:159], v66 offset:24576
	ds_read_b64_tr_b16 v[160:161], v66 offset:25088
	v_mfma_f32_32x32x16_bf16 v[50:65], v[166:169], v[126:129], v[50:65]
	v_add_f32_e32 v67, v84, v85
	v_add_f32_e32 v67, v86, v67
	v_add_f32_e32 v67, v87, v67
	v_add_f32_e32 v67, v88, v67
	v_add_f32_e32 v67, v89, v67
	v_cvt_pk_bf16_f32 v142, v84, v85
	v_cvt_pk_bf16_f32 v143, v86, v87
	ds_read_b64_tr_b16 v[84:85], v66 offset:28672
	ds_read_b64_tr_b16 v[86:87], v66 offset:29184
	v_mfma_f32_32x32x16_bf16 v[34:49], v[162:165], v[126:129], v[34:49]
	v_add_f32_e32 v67, v90, v67
	v_add_f32_e32 v67, v91, v67
	v_add_f32_e32 v67, v92, v67
	v_add_f32_e32 v67, v93, v67
	v_cvt_pk_bf16_f32 v144, v88, v89
	v_cvt_pk_bf16_f32 v145, v90, v91
	ds_read_b64_tr_b16 v[88:89], v66 offset:25600
	ds_read_b64_tr_b16 v[90:91], v66 offset:26112
	v_mfma_f32_32x32x16_bf16 v[50:65], v[154:157], v[122:125], v[50:65]
	v_add_f32_e32 v67, v94, v67
	v_add_f32_e32 v67, v95, v67
	v_add_f32_e32 v67, v96, v67
	v_add_f32_e32 v67, v97, v67
	v_cvt_pk_bf16_f32 v138, v92, v93
	v_cvt_pk_bf16_f32 v139, v94, v95
	ds_read_b64_tr_b16 v[92:93], v66 offset:29696
	ds_read_b64_tr_b16 v[94:95], v66 offset:30208
	v_mfma_f32_32x32x16_bf16 v[34:49], v[150:153], v[122:125], v[34:49]
	v_add_f32_e32 v67, v98, v67
	v_add_f32_e32 v67, v99, v67
	v_add_f32_e32 v67, v68, v67
	v_add_f32_e32 v67, v69, v67
	v_cvt_pk_bf16_f32 v140, v96, v97
	v_cvt_pk_bf16_f32 v141, v98, v99
	ds_read_b64_tr_b16 v[96:97], v66 offset:26624
	ds_read_b64_tr_b16 v[98:99], v66 offset:27136
	v_mfma_f32_32x32x16_bf16 v[50:65], v[146:149], v[118:121], v[50:65]
	v_add_f32_e32 v67, v70, v67
	v_add_f32_e32 v67, v71, v67
	v_add_f32_e32 v67, v72, v67
	v_add_f32_e32 v67, v73, v67
	v_cvt_pk_bf16_f32 v134, v68, v69
	v_cvt_pk_bf16_f32 v135, v70, v71
	ds_read_b64_tr_b16 v[68:69], v66 offset:30720
	ds_read_b64_tr_b16 v[70:71], v66 offset:31232
	v_mfma_f32_32x32x16_bf16 v[34:49], v[108:111], v[118:121], v[34:49]
	v_add_f32_e32 v67, v74, v67
	v_add_f32_e32 v67, v75, v67
	v_add_f32_e32 v67, v76, v67
	v_add_f32_e32 v67, v77, v67
	v_cvt_pk_bf16_f32 v136, v72, v73
	v_cvt_pk_bf16_f32 v137, v74, v75
	ds_read_b64_tr_b16 v[72:73], v66 offset:27648
	ds_read_b64_tr_b16 v[74:75], v66 offset:28160
	v_mfma_f32_32x32x16_bf16 v[50:65], v[104:107], v[114:117], v[50:65]
	v_add_f32_e32 v67, v78, v67
	v_add_f32_e32 v67, v79, v67
	v_add_f32_e32 v67, v80, v67
	v_add_f32_e32 v67, v81, v67
	v_cvt_pk_bf16_f32 v130, v76, v77
	v_cvt_pk_bf16_f32 v131, v78, v79
	ds_read_b64_tr_b16 v[76:77], v66 offset:31744
	ds_read_b64_tr_b16 v[78:79], v66 offset:32256
	v_mfma_f32_32x32x16_bf16 v[34:49], v[100:103], v[114:117], v[34:49]
	v_add_f32_e32 v66, v82, v67
	v_add_f32_e32 v66, v83, v66
	v_add_f32_e32 v104, 0, v66
	v_cvt_pk_bf16_f32 v132, v80, v81
	v_cvt_pk_bf16_f32 v133, v82, v83
	s_ashr_i32 s9, s8, 31
	s_lshl_b64 s[44:45], s[8:9], 17
	s_add_i32 s9, s50, s69
	s_cmp_lt_u32 s72, 2
	s_cselect_b32 s2, s2, s8
	s_add_i32 s8, s2, -2
	v_lshl_add_u64 v[66:67], v[182:183], 0, s[44:45]
	s_mov_b32 s44, m0
	s_mov_b32 m0, s9
	s_nop 0
	global_load_lds_dwordx4 v[66:67], off
	s_mov_b32 m0, s44
	s_ashr_i32 s9, s8, 31
	s_lshl_b64 s[8:9], s[8:9], 17
	v_lshl_add_u64 v[66:67], v[184:185], 0, s[8:9]
	s_add_i32 s2, s18, s70
	s_mov_b32 s8, m0
	s_mov_b32 m0, s2
	s_nop 0
	global_load_lds_dwordx4 v[66:67], off
	s_mov_b32 m0, s8
	s_cmp_lg_u32 s100, 0
	s_cbranch_scc0 .Lmx_full1
	v_add_f32_e32 v66, v0, v104
	s_mov_b64 s[8:9], 0
	s_branch .LBB0_623
.Lmx_full1:
	v_max_f32_e32 v66, v51, v51
	v_max_f32_e32 v67, v50, v50
	v_max_f32_e32 v66, v67, v66
	v_max3_f32 v67, v52, v53, v35
	v_max3_f32 v66, v66, v34, v36
	v_max3_f32 v66, v66, v37, v54
	v_max3_f32 v67, v67, v56, v57
	v_max3_f32 v66, v66, v55, v38
	v_max3_f32 v67, v67, v40, v41
	v_max3_f32 v66, v66, v39, v58
	v_max3_f32 v67, v67, v60, v61
	v_max3_f32 v66, v66, v59, v42
	v_max3_f32 v67, v67, v44, v45
	v_max3_f32 v66, v66, v43, v62
	v_max3_f32 v67, v67, v64, v65
	v_max3_f32 v80, v66, v63, v46
	v_max3_f32 v67, v67, v48, v49
	v_add_f32_e32 v66, v0, v104
	v_max3_f32 v0, v80, v47, v67
	v_mov_b32_e32 v67, v0
	s_nop 1
	v_permlane32_swap_b32_e32 v0, v67
	v_max_f32_e32 v67, v67, v67
	v_max_f32_e32 v0, v0, v0
	v_max_f32_e32 v0, v0, v67
	v_cmp_lt_f32_e32 vcc, s92, v0
	s_cmp_lg_u64 vcc, 0
	s_cselect_b64 s[8:9], -1, 0
	s_cbranch_vccnz .LBB0_630
